# static s_setprio 1 for the younger half of workgroups (id>=256), on top of interleaved GEMM loops: slower
# baseline (speedup 1.0000x reference)
_Z14fwd_megakernel6Params:
	s_load_dwordx8 s[24:31], s[0:1], 0x40
	s_load_dwordx2 s[34:35], s[0:1], 0x60
	s_add_u32 s6, s0, 0x60
	s_addc_u32 s7, s1, 0
	s_mov_b32 s66, s2
	s_cmp_lt_u32 s2, 0x100
	s_cbranch_scc1 .Lprio_older
	s_setprio 1
.Lprio_older:
	s_waitcnt lgkmcnt(0)
	s_cmp_eq_u64 s[30:31], 0
	s_mov_b64 s[4:5], 0
	s_cbranch_scc1 .LBB0_2
	v_and_b32_e32 v254, 0x3ff, v0
	s_branch .LBB0_3
